# P4 V^T copy: G==256 path with all 8 items' loads issued up front and the 8 iterations unrolled (rolled loop was load-latency bound)
# speedup vs baseline: 1.0066x; 1.0066x over previous
; #define LAS __attribute__((address_space(3)))
; __global__ void __launch_bounds__(512, 2) fwd_mega(Args args) {
;     ...
;             { LAS bf16* T = (LAS bf16*)lds; const int r = tid >> 3, j = tid & 7, dd = tid & 127, kq = tid >> 7;
;               int idx = bx; u32x4 ta = {0u, 0u, 0u, 0u}, tb = {0u, 0u, 0u, 0u};
;               if (idx < 2048) { const int rem = idx & 1023, b_ = rem >> 8, hq = (rem >> 5) & 7, st = rem & 31; const bf16* p = PROJ + (size_t)(b_ * SEQ + 64 * st + r) * PROJW + ((idx >> 10) ? 4096 : 2048) + 128 * hq + 8 * j;
;                   ta = *(const u32x4*)p; tb = *(const u32x4*)(p + 64); }
;               for (; idx < 2048; idx += G) {
;                   *(LAS u32x4*)(T + r * QP + 8 * j) = ta; *(LAS u32x4*)(T + r * QP + 64 + 8 * j) = tb;
;                   __syncthreads();
;                   if (idx + G < 2048) { const int i2 = idx + G, rem = i2 & 1023, b_ = rem >> 8, hq = (rem >> 5) & 7, st = rem & 31; const bf16* p = PROJ + (size_t)(b_ * SEQ + 64 * st + r) * PROJW + ((i2 >> 10) ? 4096 : 2048) + 128 * hq + 8 * j;
;                       ta = *(const u32x4*)p; tb = *(const u32x4*)(p + 64); }
.LBB0_141:
	v_readlane_b32 s10, v253, 10
	v_readlane_b32 s11, v253, 11
	s_andn2_b64 vcc, exec, s[10:11]
	s_cbranch_vccnz .LBB0_153
	s_cmpk_lg_i32 s52, 0x100
	s_cbranch_scc0 .Lvt8
	v_ashrrev_i32_e32 v9, 3, v238
	v_readlane_b32 s0, v253, 14
	v_mov_b64_e32 v[0:1], s[38:39]
	v_and_b32_e32 v8, 7, v238
	v_add_u32_e32 v2, s0, v9
	v_mad_i64_i32 v[0:1], s[10:11], v2, s97, v[0:1]
	v_readlane_b32 s10, v255, 21
	s_mov_b32 s0, s10
	v_readlane_b32 s11, v255, 22
	v_writelane_b32 v255, s0, 21
	s_mov_b32 s11, s27
	v_lshl_add_u64 v[0:1], v[0:1], 0, s[10:11]
	v_writelane_b32 v255, s1, 22
	v_lshlrev_b32_e32 v152, 4, v8
	v_readlane_b32 s10, v255, 23
	v_readlane_b32 s11, v255, 24
	s_mov_b32 s11, s27
	v_ashrrev_i32_e32 v11, 7, v238
	v_lshl_add_u64 v[0:1], v[0:1], 0, s[10:11]
	v_lshl_add_u64 v[4:5], v[0:1], 0, v[152:153]
	global_load_dwordx4 v[0:3], v[4:5], off
	s_nop 0
	global_load_dwordx4 v[4:7], v[4:5], off offset:128
	s_mov_b32 s0, s10
	v_lshlrev_b32_e32 v10, 4, v11
	v_and_b32_e32 v15, 0xffffffe0, v9
	v_lshlrev_b32_e32 v11, 3, v11
	v_writelane_b32 v255, s0, 23
	v_and_b32_e32 v13, 0x7f, v238
	v_lshlrev_b32_e32 v12, 3, v8
	v_mul_lo_u32 v8, v9, s94
	v_and_or_b32 v15, v11, 8, v15
	v_writelane_b32 v255, s1, 24
	v_add3_u32 v14, 0, v8, v152
	v_lshl_add_u32 v8, v13, 1, 0
	v_lshlrev_b32_e32 v16, 11, v13
	v_ashrrev_i32_e32 v11, 31, v10
	v_or_b32_e32 v17, 4, v10
	v_or_b32_e32 v18, 16, v15
	v_or_b32_e32 v19, 5, v10
	v_or_b32_e32 v20, 17, v15
	v_or_b32_e32 v21, 6, v10
	v_or_b32_e32 v22, 18, v15
	v_or_b32_e32 v23, 7, v10
	v_or_b32_e32 v24, 19, v15
	v_or_b32_e32 v25, 8, v10
	v_or_b32_e32 v26, 4, v15
	v_or_b32_e32 v27, 9, v10
	v_or_b32_e32 v28, 5, v15
	v_or_b32_e32 v29, 10, v10
	v_or_b32_e32 v30, 6, v15
	v_or_b32_e32 v31, 11, v10
	v_or_b32_e32 v32, 7, v15
	v_or_b32_e32 v33, 12, v10
	v_or_b32_e32 v34, 20, v15
	v_or_b32_e32 v35, 13, v10
	v_or_b32_e32 v36, 21, v15
	v_or_b32_e32 v37, 14, v10
	v_or_b32_e32 v38, 22, v15
	v_or_b32_e32 v39, 15, v10
	s_waitcnt vmcnt(3)
	v_or_b32_e32 v40, 23, v15
	v_lshlrev_b32_e32 v12, 1, v12
	v_readlane_b32 s0, v254, 59
	v_readlane_b32 s14, v254, 54
	v_readlane_b32 s16, v253, 13
	v_readlane_b32 s15, v254, 53
	s_mov_b32 s23, s2
	s_waitcnt vmcnt(0)
	s_branch .LBB0_144

; #define LAS __attribute__((address_space(3)))
; __global__ void __launch_bounds__(512, 2) fwd_mega(Args args) {
;     ...
;             { LAS bf16* T = (LAS bf16*)lds; const int r = tid >> 3, j = tid & 7, dd = tid & 127, kq = tid >> 7;
;               int idx = bx; u32x4 ta = {0u, 0u, 0u, 0u}, tb = {0u, 0u, 0u, 0u};
;               if (idx < 2048) { const int rem = idx & 1023, b_ = rem >> 8, hq = (rem >> 5) & 7, st = rem & 31; const bf16* p = PROJ + (size_t)(b_ * SEQ + 64 * st + r) * PROJW + ((idx >> 10) ? 4096 : 2048) + 128 * hq + 8 * j;
;                   ta = *(const u32x4*)p; tb = *(const u32x4*)(p + 64); }
;               for (; idx < 2048; idx += G) {
;                   *(LAS u32x4*)(T + r * QP + 8 * j) = ta; *(LAS u32x4*)(T + r * QP + 64 + 8 * j) = tb;
;                   __syncthreads();
;                   if (idx + G < 2048) { const int i2 = idx + G, rem = i2 & 1023, b_ = rem >> 8, hq = (rem >> 5) & 7, st = rem & 31; const bf16* p = PROJ + (size_t)(b_ * SEQ + 64 * st + r) * PROJW + ((i2 >> 10) ? 4096 : 2048) + 128 * hq + 8 * j;
;                       ta = *(const u32x4*)p; tb = *(const u32x4*)(p + 64); }
;                   unsigned v[16];
; #pragma unroll
;                   for (int i = 0; i < 16; ++i) { const int key = (idx >> 10) ? (16 * kq + i) : (32 * (kq >> 1) + 16 * ((i >> 2) & 1) + 8 * (kq & 1) + 4 * (i >> 3) + (i & 3)); v[i] = T[key * QP + dd]; }
;                   u32x4 o0, o1; o0.x = v[0] | (v[1] << 16); o0.y = v[2] | (v[3] << 16); o0.z = v[4] | (v[5] << 16); o0.w = v[6] | (v[7] << 16);
;                   o1.x = v[8] | (v[9] << 16); o1.y = v[10] | (v[11] << 16); o1.z = v[12] | (v[13] << 16); o1.w = v[14] | (v[15] << 16);
;                   { const int rem = idx & 1023, b_ = rem >> 8, hq = (rem >> 5) & 7, st = rem & 31;
;                     bf16* dst = ((idx >> 10) ? VTG : VTA) + ((size_t)(b_ * 8 + hq) * 128 + dd) * SEQ + 64 * st + 16 * kq;
;                     *(u32x4*)dst = o0; *(u32x4*)(dst + 8) = o1; }
;                   __syncthreads();
.Lvt8:
	v_ashrrev_i32_e32 v9, 3, v238
	v_readlane_b32 s0, v253, 14
	v_mov_b64_e32 v[0:1], s[38:39]
	v_and_b32_e32 v8, 7, v238
	v_add_u32_e32 v2, s0, v9
	v_mad_i64_i32 v[0:1], s[10:11], v2, s97, v[0:1]
	v_readlane_b32 s10, v255, 21
	s_mov_b32 s0, s10
	v_readlane_b32 s11, v255, 22
	v_writelane_b32 v255, s0, 21
	s_mov_b32 s11, s27
	v_lshl_add_u64 v[0:1], v[0:1], 0, s[10:11]
	v_writelane_b32 v255, s1, 22
	v_lshlrev_b32_e32 v152, 4, v8
	v_readlane_b32 s10, v255, 23
	v_readlane_b32 s11, v255, 24
	s_mov_b32 s11, s27
	v_ashrrev_i32_e32 v11, 7, v238
	v_lshl_add_u64 v[0:1], v[0:1], 0, s[10:11]
	v_lshl_add_u64 v[134:135], v[0:1], 0, v[152:153]
	s_mov_b64 s[24:25], 0x1800000
	s_mov_b64 s[36:37], 0x1000
	v_lshl_add_u64 v[136:137], v[134:135], 0, s[24:25]
	v_lshl_add_u64 v[138:139], v[136:137], 0, s[24:25]
	v_lshl_add_u64 v[140:141], v[138:139], 0, s[24:25]
	v_lshl_add_u64 v[142:143], v[134:135], 0, s[36:37]
	v_lshl_add_u64 v[144:145], v[136:137], 0, s[36:37]
	v_lshl_add_u64 v[146:147], v[138:139], 0, s[36:37]
	v_lshl_add_u64 v[148:149], v[140:141], 0, s[36:37]
	global_load_dwordx4 v[60:63], v[134:135], off
	global_load_dwordx4 v[64:67], v[134:135], off offset:128
	global_load_dwordx4 v[68:71], v[136:137], off
	global_load_dwordx4 v[72:75], v[136:137], off offset:128
	global_load_dwordx4 v[76:79], v[138:139], off
	global_load_dwordx4 v[80:83], v[138:139], off offset:128
	global_load_dwordx4 v[84:87], v[140:141], off
	global_load_dwordx4 v[88:91], v[140:141], off offset:128
	global_load_dwordx4 v[92:95], v[142:143], off
	global_load_dwordx4 v[96:99], v[142:143], off offset:128
	global_load_dwordx4 v[108:111], v[144:145], off
	global_load_dwordx4 v[112:115], v[144:145], off offset:128
	global_load_dwordx4 v[116:119], v[146:147], off
	global_load_dwordx4 v[120:123], v[146:147], off offset:128
	global_load_dwordx4 v[126:129], v[148:149], off
	global_load_dwordx4 v[130:133], v[148:149], off offset:128
	s_mov_b32 s0, s10
	v_lshlrev_b32_e32 v10, 4, v11
	v_and_b32_e32 v15, 0xffffffe0, v9
	v_lshlrev_b32_e32 v11, 3, v11
	v_writelane_b32 v255, s0, 23
	v_and_b32_e32 v13, 0x7f, v238
	v_lshlrev_b32_e32 v12, 3, v8
	v_mul_lo_u32 v8, v9, s94
	v_and_or_b32 v15, v11, 8, v15
	v_writelane_b32 v255, s1, 24
	v_add3_u32 v14, 0, v8, v152
	v_lshl_add_u32 v8, v13, 1, 0
	v_lshlrev_b32_e32 v16, 11, v13
	v_ashrrev_i32_e32 v11, 31, v10
	v_or_b32_e32 v17, 4, v10
	v_or_b32_e32 v18, 16, v15
	v_or_b32_e32 v19, 5, v10
	v_or_b32_e32 v20, 17, v15
	v_or_b32_e32 v21, 6, v10
	v_or_b32_e32 v22, 18, v15
	v_or_b32_e32 v23, 7, v10
	v_or_b32_e32 v24, 19, v15
	v_or_b32_e32 v25, 8, v10
	v_or_b32_e32 v26, 4, v15
	v_or_b32_e32 v27, 9, v10
	v_or_b32_e32 v28, 5, v15
	v_or_b32_e32 v29, 10, v10
	v_or_b32_e32 v30, 6, v15
	v_or_b32_e32 v31, 11, v10
	v_or_b32_e32 v32, 7, v15
	v_or_b32_e32 v33, 12, v10
	v_or_b32_e32 v34, 20, v15
	v_or_b32_e32 v35, 13, v10
	v_or_b32_e32 v36, 21, v15
	v_or_b32_e32 v37, 14, v10
	v_or_b32_e32 v38, 22, v15
	v_or_b32_e32 v39, 15, v10
	v_or_b32_e32 v40, 23, v15
	v_lshlrev_b32_e32 v12, 1, v12
	v_readlane_b32 s0, v254, 59
	v_readlane_b32 s14, v254, 54
	v_readlane_b32 s16, v253, 13
	v_readlane_b32 s15, v254, 53
	s_mov_b32 s23, s2
	s_add_i32 s17, s23, s52
	s_cmpk_gt_i32 s17, 0x7ff
	s_cselect_b64 s[10:11], -1, 0
	s_waitcnt vmcnt(14)
	ds_write_b128 v14, v[60:63]
	ds_write_b128 v14, v[64:67] offset:128
	s_waitcnt lgkmcnt(0)
	s_barrier
	v_readlane_b32 s22, v254, 57
	s_add_i32 s22, s16, s22
	s_cmpk_lt_u32 s23, 0x400
	s_cselect_b64 vcc, -1, 0
	v_cndmask_b32_e32 v13, v10, v15, vcc
	v_mad_u64_u32 v[42:43], s[24:25], v13, s94, v[8:9]
	ds_read_u16 v13, v42
	ds_read_u16 v41, v42 offset:288
	ds_read_u16 v44, v42 offset:576
	ds_read_u16 v45, v42 offset:864
	v_cndmask_b32_e32 v42, v17, v18, vcc
	v_mad_u64_u32 v[42:43], s[24:25], v42, s94, v[8:9]
	ds_read_u16 v46, v42
	v_cndmask_b32_e32 v42, v19, v20, vcc
	v_mad_u64_u32 v[42:43], s[24:25], v42, s94, v[8:9]
	ds_read_u16 v47, v42
	v_cndmask_b32_e32 v42, v21, v22, vcc
	v_mad_u64_u32 v[42:43], s[24:25], v42, s94, v[8:9]
	ds_read_u16 v48, v42
	v_cndmask_b32_e32 v42, v23, v24, vcc
	v_mad_u64_u32 v[42:43], s[24:25], v42, s94, v[8:9]
	ds_read_u16 v49, v42
	v_cndmask_b32_e32 v42, v25, v26, vcc
	v_mad_u64_u32 v[42:43], s[24:25], v42, s94, v[8:9]
	ds_read_u16 v50, v42
	v_cndmask_b32_e32 v42, v27, v28, vcc
	v_mad_u64_u32 v[42:43], s[24:25], v42, s94, v[8:9]
	ds_read_u16 v51, v42
	v_cndmask_b32_e32 v42, v29, v30, vcc
	v_mad_u64_u32 v[42:43], s[24:25], v42, s94, v[8:9]
	ds_read_u16 v52, v42
	v_cndmask_b32_e32 v42, v31, v32, vcc
	v_mad_u64_u32 v[42:43], s[24:25], v42, s94, v[8:9]
	ds_read_u16 v53, v42
	v_cndmask_b32_e32 v42, v33, v34, vcc
	v_mad_u64_u32 v[42:43], s[24:25], v42, s94, v[8:9]
	ds_read_u16 v54, v42
	v_cndmask_b32_e32 v42, v35, v36, vcc
	v_mad_u64_u32 v[42:43], s[24:25], v42, s94, v[8:9]
	ds_read_u16 v55, v42
	v_cndmask_b32_e32 v42, v37, v38, vcc
	v_mad_u64_u32 v[42:43], s[24:25], v42, s94, v[8:9]
	ds_read_u16 v56, v42
	s_and_b64 s[24:25], vcc, exec
	v_cndmask_b32_e32 v42, v39, v40, vcc
	s_cselect_b32 s25, s29, s80
	s_cselect_b32 s24, s28, s71
	v_mad_u64_u32 v[42:43], s[36:37], v42, s94, v[8:9]
	s_and_b32 s23, s0, 0x7c0000
	ds_read_u16 v57, v42
	s_waitcnt lgkmcnt(14)
	v_lshl_or_b32 v42, v41, 16, v13
	v_or_b32_e32 v13, s23, v16
	v_lshlrev_b32_e32 v152, 1, v13
	s_and_b32 s16, s16, 0x7c0
	s_waitcnt lgkmcnt(12)
	v_lshl_or_b32 v43, v45, 16, v44
	s_waitcnt lgkmcnt(10)
	v_lshl_or_b32 v44, v47, 16, v46
	s_waitcnt lgkmcnt(6)
	v_lshl_or_b32 v46, v51, 16, v50
	v_lshl_add_u64 v[50:51], s[24:25], 0, v[152:153]
	s_lshl_b32 s26, s16, 1
	v_readlane_b32 s16, v254, 58
	v_lshl_add_u64 v[50:51], v[50:51], 0, s[26:27]
	s_add_i32 s14, s14, s16
	v_readlane_b32 s16, v254, 60
	v_lshl_or_b32 v45, v49, 16, v48
	v_lshl_add_u64 v[50:51], v[10:11], 1, v[50:51]
	s_add_i32 s15, s15, s33
	s_add_i32 s0, s0, s16
	s_and_b64 vcc, exec, s[10:11]
	s_mov_b32 s16, s22
	s_mov_b32 s23, s17
	s_waitcnt lgkmcnt(4)
	v_lshl_or_b32 v47, v53, 16, v52
	s_waitcnt lgkmcnt(2)
	v_lshl_or_b32 v48, v55, 16, v54
	s_waitcnt lgkmcnt(0)
	v_lshl_or_b32 v49, v57, 16, v56
	global_store_dwordx4 v[50:51], v[42:45], off
	global_store_dwordx4 v[50:51], v[46:49], off offset:16
	s_barrier
; #define LAS __attribute__((address_space(3)))
; __global__ void __launch_bounds__(512, 2) fwd_mega(Args args) {
;     ...
;               for (; idx < 2048; idx += G) {
;                   *(LAS u32x4*)(T + r * QP + 8 * j) = ta; *(LAS u32x4*)(T + r * QP + 64 + 8 * j) = tb;
;                   __syncthreads();
;                   if (idx + G < 2048) { const int i2 = idx + G, rem = i2 & 1023, b_ = rem >> 8, hq = (rem >> 5) & 7, st = rem & 31; const bf16* p = PROJ + (size_t)(b_ * SEQ + 64 * st + r) * PROJW + ((i2 >> 10) ? 4096 : 2048) + 128 * hq + 8 * j;
;                       ta = *(const u32x4*)p; tb = *(const u32x4*)(p + 64); }
;                   unsigned v[16];
; #pragma unroll
;                   for (int i = 0; i < 16; ++i) { const int key = (idx >> 10) ? (16 * kq + i) : (32 * (kq >> 1) + 16 * ((i >> 2) & 1) + 8 * (kq & 1) + 4 * (i >> 3) + (i & 3)); v[i] = T[key * QP + dd]; }
;                   u32x4 o0, o1; o0.x = v[0] | (v[1] << 16); o0.y = v[2] | (v[3] << 16); o0.z = v[4] | (v[5] << 16); o0.w = v[6] | (v[7] << 16);
;                   o1.x = v[8] | (v[9] << 16); o1.y = v[10] | (v[11] << 16); o1.z = v[12] | (v[13] << 16); o1.w = v[14] | (v[15] << 16);
;                   { const int rem = idx & 1023, b_ = rem >> 8, hq = (rem >> 5) & 7, st = rem & 31;
;                     bf16* dst = ((idx >> 10) ? VTG : VTA) + ((size_t)(b_ * 8 + hq) * 128 + dd) * SEQ + 64 * st + 16 * kq;
;                     *(u32x4*)dst = o0; *(u32x4*)(dst + 8) = o1; }
;                   __syncthreads();
	s_add_i32 s17, s23, s52
	s_cmpk_gt_i32 s17, 0x7ff
	s_cselect_b64 s[10:11], -1, 0
	s_waitcnt vmcnt(14)
	ds_write_b128 v14, v[68:71]
	ds_write_b128 v14, v[72:75] offset:128
	s_waitcnt lgkmcnt(0)
	s_barrier
	v_readlane_b32 s22, v254, 57
	s_add_i32 s22, s16, s22
	s_cmpk_lt_u32 s23, 0x400
	s_cselect_b64 vcc, -1, 0
	v_cndmask_b32_e32 v13, v10, v15, vcc
	v_mad_u64_u32 v[42:43], s[24:25], v13, s94, v[8:9]
	ds_read_u16 v13, v42
	ds_read_u16 v41, v42 offset:288
	ds_read_u16 v44, v42 offset:576
	ds_read_u16 v45, v42 offset:864
	v_cndmask_b32_e32 v42, v17, v18, vcc
	v_mad_u64_u32 v[42:43], s[24:25], v42, s94, v[8:9]
	ds_read_u16 v46, v42
	v_cndmask_b32_e32 v42, v19, v20, vcc
	v_mad_u64_u32 v[42:43], s[24:25], v42, s94, v[8:9]
	ds_read_u16 v47, v42
	v_cndmask_b32_e32 v42, v21, v22, vcc
	v_mad_u64_u32 v[42:43], s[24:25], v42, s94, v[8:9]
	ds_read_u16 v48, v42
	v_cndmask_b32_e32 v42, v23, v24, vcc
	v_mad_u64_u32 v[42:43], s[24:25], v42, s94, v[8:9]
	ds_read_u16 v49, v42
	v_cndmask_b32_e32 v42, v25, v26, vcc
	v_mad_u64_u32 v[42:43], s[24:25], v42, s94, v[8:9]
	ds_read_u16 v50, v42
	v_cndmask_b32_e32 v42, v27, v28, vcc
	v_mad_u64_u32 v[42:43], s[24:25], v42, s94, v[8:9]
	ds_read_u16 v51, v42
	v_cndmask_b32_e32 v42, v29, v30, vcc
	v_mad_u64_u32 v[42:43], s[24:25], v42, s94, v[8:9]
	ds_read_u16 v52, v42
	v_cndmask_b32_e32 v42, v31, v32, vcc
	v_mad_u64_u32 v[42:43], s[24:25], v42, s94, v[8:9]
	ds_read_u16 v53, v42
	v_cndmask_b32_e32 v42, v33, v34, vcc
	v_mad_u64_u32 v[42:43], s[24:25], v42, s94, v[8:9]
	ds_read_u16 v54, v42
	v_cndmask_b32_e32 v42, v35, v36, vcc
	v_mad_u64_u32 v[42:43], s[24:25], v42, s94, v[8:9]
	ds_read_u16 v55, v42
	v_cndmask_b32_e32 v42, v37, v38, vcc
	v_mad_u64_u32 v[42:43], s[24:25], v42, s94, v[8:9]
	ds_read_u16 v56, v42
	s_and_b64 s[24:25], vcc, exec
	v_cndmask_b32_e32 v42, v39, v40, vcc
	s_cselect_b32 s25, s29, s80
	s_cselect_b32 s24, s28, s71
	v_mad_u64_u32 v[42:43], s[36:37], v42, s94, v[8:9]
	s_and_b32 s23, s0, 0x7c0000
	ds_read_u16 v57, v42
	s_waitcnt lgkmcnt(14)
	v_lshl_or_b32 v42, v41, 16, v13
	v_or_b32_e32 v13, s23, v16
	v_lshlrev_b32_e32 v152, 1, v13
	s_and_b32 s16, s16, 0x7c0
	s_waitcnt lgkmcnt(12)
	v_lshl_or_b32 v43, v45, 16, v44
	s_waitcnt lgkmcnt(10)
	v_lshl_or_b32 v44, v47, 16, v46
	s_waitcnt lgkmcnt(6)
	v_lshl_or_b32 v46, v51, 16, v50
	v_lshl_add_u64 v[50:51], s[24:25], 0, v[152:153]
	s_lshl_b32 s26, s16, 1
	v_readlane_b32 s16, v254, 58
	v_lshl_add_u64 v[50:51], v[50:51], 0, s[26:27]
	s_add_i32 s14, s14, s16
	v_readlane_b32 s16, v254, 60
	v_lshl_or_b32 v45, v49, 16, v48
	v_lshl_add_u64 v[50:51], v[10:11], 1, v[50:51]
	s_add_i32 s15, s15, s33
	s_add_i32 s0, s0, s16
	s_and_b64 vcc, exec, s[10:11]
	s_mov_b32 s16, s22
	s_mov_b32 s23, s17
	s_waitcnt lgkmcnt(4)
	v_lshl_or_b32 v47, v53, 16, v52
	s_waitcnt lgkmcnt(2)
	v_lshl_or_b32 v48, v55, 16, v54
	s_waitcnt lgkmcnt(0)
	v_lshl_or_b32 v49, v57, 16, v56
	global_store_dwordx4 v[50:51], v[42:45], off
	global_store_dwordx4 v[50:51], v[46:49], off offset:16
	s_barrier
	s_add_i32 s17, s23, s52
	s_cmpk_gt_i32 s17, 0x7ff
	s_cselect_b64 s[10:11], -1, 0
	s_waitcnt vmcnt(14)
	ds_write_b128 v14, v[76:79]
	ds_write_b128 v14, v[80:83] offset:128
	s_waitcnt lgkmcnt(0)
	s_barrier
	v_readlane_b32 s22, v254, 57
	s_add_i32 s22, s16, s22
	s_cmpk_lt_u32 s23, 0x400
	s_cselect_b64 vcc, -1, 0
	v_cndmask_b32_e32 v13, v10, v15, vcc
	v_mad_u64_u32 v[42:43], s[24:25], v13, s94, v[8:9]
	ds_read_u16 v13, v42
	ds_read_u16 v41, v42 offset:288
	ds_read_u16 v44, v42 offset:576
	ds_read_u16 v45, v42 offset:864
	v_cndmask_b32_e32 v42, v17, v18, vcc
	v_mad_u64_u32 v[42:43], s[24:25], v42, s94, v[8:9]
	ds_read_u16 v46, v42
	v_cndmask_b32_e32 v42, v19, v20, vcc
	v_mad_u64_u32 v[42:43], s[24:25], v42, s94, v[8:9]
	ds_read_u16 v47, v42
	v_cndmask_b32_e32 v42, v21, v22, vcc
	v_mad_u64_u32 v[42:43], s[24:25], v42, s94, v[8:9]
	ds_read_u16 v48, v42
	v_cndmask_b32_e32 v42, v23, v24, vcc
	v_mad_u64_u32 v[42:43], s[24:25], v42, s94, v[8:9]
	ds_read_u16 v49, v42
	v_cndmask_b32_e32 v42, v25, v26, vcc
	v_mad_u64_u32 v[42:43], s[24:25], v42, s94, v[8:9]
	ds_read_u16 v50, v42
	v_cndmask_b32_e32 v42, v27, v28, vcc
	v_mad_u64_u32 v[42:43], s[24:25], v42, s94, v[8:9]
	ds_read_u16 v51, v42
	v_cndmask_b32_e32 v42, v29, v30, vcc
	v_mad_u64_u32 v[42:43], s[24:25], v42, s94, v[8:9]
	ds_read_u16 v52, v42
	v_cndmask_b32_e32 v42, v31, v32, vcc
	v_mad_u64_u32 v[42:43], s[24:25], v42, s94, v[8:9]
	ds_read_u16 v53, v42
	v_cndmask_b32_e32 v42, v33, v34, vcc
	v_mad_u64_u32 v[42:43], s[24:25], v42, s94, v[8:9]
	ds_read_u16 v54, v42
	v_cndmask_b32_e32 v42, v35, v36, vcc
	v_mad_u64_u32 v[42:43], s[24:25], v42, s94, v[8:9]
	ds_read_u16 v55, v42
	v_cndmask_b32_e32 v42, v37, v38, vcc
	v_mad_u64_u32 v[42:43], s[24:25], v42, s94, v[8:9]
	ds_read_u16 v56, v42
	s_and_b64 s[24:25], vcc, exec
	v_cndmask_b32_e32 v42, v39, v40, vcc
	s_cselect_b32 s25, s29, s80
	s_cselect_b32 s24, s28, s71
	v_mad_u64_u32 v[42:43], s[36:37], v42, s94, v[8:9]
	s_and_b32 s23, s0, 0x7c0000
	ds_read_u16 v57, v42
	s_waitcnt lgkmcnt(14)
	v_lshl_or_b32 v42, v41, 16, v13
	v_or_b32_e32 v13, s23, v16
	v_lshlrev_b32_e32 v152, 1, v13
	s_and_b32 s16, s16, 0x7c0
	s_waitcnt lgkmcnt(12)
	v_lshl_or_b32 v43, v45, 16, v44
	s_waitcnt lgkmcnt(10)
	v_lshl_or_b32 v44, v47, 16, v46
	s_waitcnt lgkmcnt(6)
	v_lshl_or_b32 v46, v51, 16, v50
	v_lshl_add_u64 v[50:51], s[24:25], 0, v[152:153]
	s_lshl_b32 s26, s16, 1
	v_readlane_b32 s16, v254, 58
	v_lshl_add_u64 v[50:51], v[50:51], 0, s[26:27]
	s_add_i32 s14, s14, s16
	v_readlane_b32 s16, v254, 60
	v_lshl_or_b32 v45, v49, 16, v48
	v_lshl_add_u64 v[50:51], v[10:11], 1, v[50:51]
	s_add_i32 s15, s15, s33
	s_add_i32 s0, s0, s16
	s_and_b64 vcc, exec, s[10:11]
	s_mov_b32 s16, s22
	s_mov_b32 s23, s17
	s_waitcnt lgkmcnt(4)
	v_lshl_or_b32 v47, v53, 16, v52
	s_waitcnt lgkmcnt(2)
	v_lshl_or_b32 v48, v55, 16, v54
	s_waitcnt lgkmcnt(0)
	v_lshl_or_b32 v49, v57, 16, v56
	global_store_dwordx4 v[50:51], v[42:45], off
	global_store_dwordx4 v[50:51], v[46:49], off offset:16
	s_barrier
; #define LAS __attribute__((address_space(3)))
; __global__ void __launch_bounds__(512, 2) fwd_mega(Args args) {
;     ...
;               for (; idx < 2048; idx += G) {
;                   *(LAS u32x4*)(T + r * QP + 8 * j) = ta; *(LAS u32x4*)(T + r * QP + 64 + 8 * j) = tb;
;                   __syncthreads();
;                   if (idx + G < 2048) { const int i2 = idx + G, rem = i2 & 1023, b_ = rem >> 8, hq = (rem >> 5) & 7, st = rem & 31; const bf16* p = PROJ + (size_t)(b_ * SEQ + 64 * st + r) * PROJW + ((i2 >> 10) ? 4096 : 2048) + 128 * hq + 8 * j;
;                       ta = *(const u32x4*)p; tb = *(const u32x4*)(p + 64); }
;                   unsigned v[16];
; #pragma unroll
;                   for (int i = 0; i < 16; ++i) { const int key = (idx >> 10) ? (16 * kq + i) : (32 * (kq >> 1) + 16 * ((i >> 2) & 1) + 8 * (kq & 1) + 4 * (i >> 3) + (i & 3)); v[i] = T[key * QP + dd]; }
;                   u32x4 o0, o1; o0.x = v[0] | (v[1] << 16); o0.y = v[2] | (v[3] << 16); o0.z = v[4] | (v[5] << 16); o0.w = v[6] | (v[7] << 16);
;                   o1.x = v[8] | (v[9] << 16); o1.y = v[10] | (v[11] << 16); o1.z = v[12] | (v[13] << 16); o1.w = v[14] | (v[15] << 16);
;                   { const int rem = idx & 1023, b_ = rem >> 8, hq = (rem >> 5) & 7, st = rem & 31;
;                     bf16* dst = ((idx >> 10) ? VTG : VTA) + ((size_t)(b_ * 8 + hq) * 128 + dd) * SEQ + 64 * st + 16 * kq;
;                     *(u32x4*)dst = o0; *(u32x4*)(dst + 8) = o1; }
;                   __syncthreads();
	s_add_i32 s17, s23, s52
	s_cmpk_gt_i32 s17, 0x7ff
	s_cselect_b64 s[10:11], -1, 0
	s_waitcnt vmcnt(14)
	ds_write_b128 v14, v[84:87]
	ds_write_b128 v14, v[88:91] offset:128
	s_waitcnt lgkmcnt(0)
	s_barrier
	v_readlane_b32 s22, v254, 57
	s_add_i32 s22, s16, s22
	s_cmpk_lt_u32 s23, 0x400
	s_cselect_b64 vcc, -1, 0
	v_cndmask_b32_e32 v13, v10, v15, vcc
	v_mad_u64_u32 v[42:43], s[24:25], v13, s94, v[8:9]
	ds_read_u16 v13, v42
	ds_read_u16 v41, v42 offset:288
	ds_read_u16 v44, v42 offset:576
	ds_read_u16 v45, v42 offset:864
	v_cndmask_b32_e32 v42, v17, v18, vcc
	v_mad_u64_u32 v[42:43], s[24:25], v42, s94, v[8:9]
	ds_read_u16 v46, v42
	v_cndmask_b32_e32 v42, v19, v20, vcc
	v_mad_u64_u32 v[42:43], s[24:25], v42, s94, v[8:9]
	ds_read_u16 v47, v42
	v_cndmask_b32_e32 v42, v21, v22, vcc
	v_mad_u64_u32 v[42:43], s[24:25], v42, s94, v[8:9]
	ds_read_u16 v48, v42
	v_cndmask_b32_e32 v42, v23, v24, vcc
	v_mad_u64_u32 v[42:43], s[24:25], v42, s94, v[8:9]
	ds_read_u16 v49, v42
	v_cndmask_b32_e32 v42, v25, v26, vcc
	v_mad_u64_u32 v[42:43], s[24:25], v42, s94, v[8:9]
	ds_read_u16 v50, v42
	v_cndmask_b32_e32 v42, v27, v28, vcc
	v_mad_u64_u32 v[42:43], s[24:25], v42, s94, v[8:9]
	ds_read_u16 v51, v42
	v_cndmask_b32_e32 v42, v29, v30, vcc
	v_mad_u64_u32 v[42:43], s[24:25], v42, s94, v[8:9]
	ds_read_u16 v52, v42
	v_cndmask_b32_e32 v42, v31, v32, vcc
	v_mad_u64_u32 v[42:43], s[24:25], v42, s94, v[8:9]
	ds_read_u16 v53, v42
	v_cndmask_b32_e32 v42, v33, v34, vcc
	v_mad_u64_u32 v[42:43], s[24:25], v42, s94, v[8:9]
	ds_read_u16 v54, v42
	v_cndmask_b32_e32 v42, v35, v36, vcc
	v_mad_u64_u32 v[42:43], s[24:25], v42, s94, v[8:9]
	ds_read_u16 v55, v42
	v_cndmask_b32_e32 v42, v37, v38, vcc
	v_mad_u64_u32 v[42:43], s[24:25], v42, s94, v[8:9]
	ds_read_u16 v56, v42
	s_and_b64 s[24:25], vcc, exec
	v_cndmask_b32_e32 v42, v39, v40, vcc
	s_cselect_b32 s25, s29, s80
	s_cselect_b32 s24, s28, s71
	v_mad_u64_u32 v[42:43], s[36:37], v42, s94, v[8:9]
	s_and_b32 s23, s0, 0x7c0000
	ds_read_u16 v57, v42
	s_waitcnt lgkmcnt(14)
	v_lshl_or_b32 v42, v41, 16, v13
	v_or_b32_e32 v13, s23, v16
	v_lshlrev_b32_e32 v152, 1, v13
	s_and_b32 s16, s16, 0x7c0
	s_waitcnt lgkmcnt(12)
	v_lshl_or_b32 v43, v45, 16, v44
	s_waitcnt lgkmcnt(10)
	v_lshl_or_b32 v44, v47, 16, v46
	s_waitcnt lgkmcnt(6)
	v_lshl_or_b32 v46, v51, 16, v50
	v_lshl_add_u64 v[50:51], s[24:25], 0, v[152:153]
	s_lshl_b32 s26, s16, 1
	v_readlane_b32 s16, v254, 58
	v_lshl_add_u64 v[50:51], v[50:51], 0, s[26:27]
	s_add_i32 s14, s14, s16
	v_readlane_b32 s16, v254, 60
	v_lshl_or_b32 v45, v49, 16, v48
	v_lshl_add_u64 v[50:51], v[10:11], 1, v[50:51]
	s_add_i32 s15, s15, s33
	s_add_i32 s0, s0, s16
	s_and_b64 vcc, exec, s[10:11]
	s_mov_b32 s16, s22
	s_mov_b32 s23, s17
	s_waitcnt lgkmcnt(4)
	v_lshl_or_b32 v47, v53, 16, v52
	s_waitcnt lgkmcnt(2)
	v_lshl_or_b32 v48, v55, 16, v54
	s_waitcnt lgkmcnt(0)
	v_lshl_or_b32 v49, v57, 16, v56
	global_store_dwordx4 v[50:51], v[42:45], off
	global_store_dwordx4 v[50:51], v[46:49], off offset:16
	s_barrier
	s_add_i32 s17, s23, s52
	s_cmpk_gt_i32 s17, 0x7ff
	s_cselect_b64 s[10:11], -1, 0
	s_waitcnt vmcnt(14)
	ds_write_b128 v14, v[92:95]
	ds_write_b128 v14, v[96:99] offset:128
	s_waitcnt lgkmcnt(0)
	s_barrier
	v_readlane_b32 s22, v254, 57
	s_add_i32 s22, s16, s22
	s_cmpk_lt_u32 s23, 0x400
	s_cselect_b64 vcc, -1, 0
	v_cndmask_b32_e32 v13, v10, v15, vcc
	v_mad_u64_u32 v[42:43], s[24:25], v13, s94, v[8:9]
	ds_read_u16 v13, v42
	ds_read_u16 v41, v42 offset:288
	ds_read_u16 v44, v42 offset:576
	ds_read_u16 v45, v42 offset:864
	v_cndmask_b32_e32 v42, v17, v18, vcc
	v_mad_u64_u32 v[42:43], s[24:25], v42, s94, v[8:9]
	ds_read_u16 v46, v42
	v_cndmask_b32_e32 v42, v19, v20, vcc
	v_mad_u64_u32 v[42:43], s[24:25], v42, s94, v[8:9]
	ds_read_u16 v47, v42
	v_cndmask_b32_e32 v42, v21, v22, vcc
	v_mad_u64_u32 v[42:43], s[24:25], v42, s94, v[8:9]
	ds_read_u16 v48, v42
	v_cndmask_b32_e32 v42, v23, v24, vcc
	v_mad_u64_u32 v[42:43], s[24:25], v42, s94, v[8:9]
	ds_read_u16 v49, v42
	v_cndmask_b32_e32 v42, v25, v26, vcc
	v_mad_u64_u32 v[42:43], s[24:25], v42, s94, v[8:9]
	ds_read_u16 v50, v42
	v_cndmask_b32_e32 v42, v27, v28, vcc
	v_mad_u64_u32 v[42:43], s[24:25], v42, s94, v[8:9]
	ds_read_u16 v51, v42
	v_cndmask_b32_e32 v42, v29, v30, vcc
	v_mad_u64_u32 v[42:43], s[24:25], v42, s94, v[8:9]
	ds_read_u16 v52, v42
	v_cndmask_b32_e32 v42, v31, v32, vcc
	v_mad_u64_u32 v[42:43], s[24:25], v42, s94, v[8:9]
	ds_read_u16 v53, v42
	v_cndmask_b32_e32 v42, v33, v34, vcc
	v_mad_u64_u32 v[42:43], s[24:25], v42, s94, v[8:9]
	ds_read_u16 v54, v42
	v_cndmask_b32_e32 v42, v35, v36, vcc
	v_mad_u64_u32 v[42:43], s[24:25], v42, s94, v[8:9]
	ds_read_u16 v55, v42
	v_cndmask_b32_e32 v42, v37, v38, vcc
	v_mad_u64_u32 v[42:43], s[24:25], v42, s94, v[8:9]
	ds_read_u16 v56, v42
	s_and_b64 s[24:25], vcc, exec
	v_cndmask_b32_e32 v42, v39, v40, vcc
	s_cselect_b32 s25, s29, s80
	s_cselect_b32 s24, s28, s71
	v_mad_u64_u32 v[42:43], s[36:37], v42, s94, v[8:9]
	s_and_b32 s23, s0, 0x7c0000
	ds_read_u16 v57, v42
	s_waitcnt lgkmcnt(14)
	v_lshl_or_b32 v42, v41, 16, v13
	v_or_b32_e32 v13, s23, v16
	v_lshlrev_b32_e32 v152, 1, v13
	s_and_b32 s16, s16, 0x7c0
	s_waitcnt lgkmcnt(12)
	v_lshl_or_b32 v43, v45, 16, v44
	s_waitcnt lgkmcnt(10)
	v_lshl_or_b32 v44, v47, 16, v46
	s_waitcnt lgkmcnt(6)
	v_lshl_or_b32 v46, v51, 16, v50
	v_lshl_add_u64 v[50:51], s[24:25], 0, v[152:153]
	s_lshl_b32 s26, s16, 1
	v_readlane_b32 s16, v254, 58
	v_lshl_add_u64 v[50:51], v[50:51], 0, s[26:27]
	s_add_i32 s14, s14, s16
	v_readlane_b32 s16, v254, 60
	v_lshl_or_b32 v45, v49, 16, v48
	v_lshl_add_u64 v[50:51], v[10:11], 1, v[50:51]
	s_add_i32 s15, s15, s33
	s_add_i32 s0, s0, s16
	s_and_b64 vcc, exec, s[10:11]
	s_mov_b32 s16, s22
	s_mov_b32 s23, s17
	s_waitcnt lgkmcnt(4)
	v_lshl_or_b32 v47, v53, 16, v52
	s_waitcnt lgkmcnt(2)
	v_lshl_or_b32 v48, v55, 16, v54
	s_waitcnt lgkmcnt(0)
	v_lshl_or_b32 v49, v57, 16, v56
	global_store_dwordx4 v[50:51], v[42:45], off
	global_store_dwordx4 v[50:51], v[46:49], off offset:16
	s_barrier
; #define LAS __attribute__((address_space(3)))
; __global__ void __launch_bounds__(512, 2) fwd_mega(Args args) {
;     ...
;               for (; idx < 2048; idx += G) {
;                   *(LAS u32x4*)(T + r * QP + 8 * j) = ta; *(LAS u32x4*)(T + r * QP + 64 + 8 * j) = tb;
;                   __syncthreads();
;                   if (idx + G < 2048) { const int i2 = idx + G, rem = i2 & 1023, b_ = rem >> 8, hq = (rem >> 5) & 7, st = rem & 31; const bf16* p = PROJ + (size_t)(b_ * SEQ + 64 * st + r) * PROJW + ((i2 >> 10) ? 4096 : 2048) + 128 * hq + 8 * j;
;                       ta = *(const u32x4*)p; tb = *(const u32x4*)(p + 64); }
;                   unsigned v[16];
; #pragma unroll
;                   for (int i = 0; i < 16; ++i) { const int key = (idx >> 10) ? (16 * kq + i) : (32 * (kq >> 1) + 16 * ((i >> 2) & 1) + 8 * (kq & 1) + 4 * (i >> 3) + (i & 3)); v[i] = T[key * QP + dd]; }
;                   u32x4 o0, o1; o0.x = v[0] | (v[1] << 16); o0.y = v[2] | (v[3] << 16); o0.z = v[4] | (v[5] << 16); o0.w = v[6] | (v[7] << 16);
;                   o1.x = v[8] | (v[9] << 16); o1.y = v[10] | (v[11] << 16); o1.z = v[12] | (v[13] << 16); o1.w = v[14] | (v[15] << 16);
;                   { const int rem = idx & 1023, b_ = rem >> 8, hq = (rem >> 5) & 7, st = rem & 31;
;                     bf16* dst = ((idx >> 10) ? VTG : VTA) + ((size_t)(b_ * 8 + hq) * 128 + dd) * SEQ + 64 * st + 16 * kq;
;                     *(u32x4*)dst = o0; *(u32x4*)(dst + 8) = o1; }
;                   __syncthreads();
	s_add_i32 s17, s23, s52
	s_cmpk_gt_i32 s17, 0x7ff
	s_cselect_b64 s[10:11], -1, 0
	s_waitcnt vmcnt(14)
	ds_write_b128 v14, v[108:111]
	ds_write_b128 v14, v[112:115] offset:128
	s_waitcnt lgkmcnt(0)
	s_barrier
	v_readlane_b32 s22, v254, 57
	s_add_i32 s22, s16, s22
	s_cmpk_lt_u32 s23, 0x400
	s_cselect_b64 vcc, -1, 0
	v_cndmask_b32_e32 v13, v10, v15, vcc
	v_mad_u64_u32 v[42:43], s[24:25], v13, s94, v[8:9]
	ds_read_u16 v13, v42
	ds_read_u16 v41, v42 offset:288
	ds_read_u16 v44, v42 offset:576
	ds_read_u16 v45, v42 offset:864
	v_cndmask_b32_e32 v42, v17, v18, vcc
	v_mad_u64_u32 v[42:43], s[24:25], v42, s94, v[8:9]
	ds_read_u16 v46, v42
	v_cndmask_b32_e32 v42, v19, v20, vcc
	v_mad_u64_u32 v[42:43], s[24:25], v42, s94, v[8:9]
	ds_read_u16 v47, v42
	v_cndmask_b32_e32 v42, v21, v22, vcc
	v_mad_u64_u32 v[42:43], s[24:25], v42, s94, v[8:9]
	ds_read_u16 v48, v42
	v_cndmask_b32_e32 v42, v23, v24, vcc
	v_mad_u64_u32 v[42:43], s[24:25], v42, s94, v[8:9]
	ds_read_u16 v49, v42
	v_cndmask_b32_e32 v42, v25, v26, vcc
	v_mad_u64_u32 v[42:43], s[24:25], v42, s94, v[8:9]
	ds_read_u16 v50, v42
	v_cndmask_b32_e32 v42, v27, v28, vcc
	v_mad_u64_u32 v[42:43], s[24:25], v42, s94, v[8:9]
	ds_read_u16 v51, v42
	v_cndmask_b32_e32 v42, v29, v30, vcc
	v_mad_u64_u32 v[42:43], s[24:25], v42, s94, v[8:9]
	ds_read_u16 v52, v42
	v_cndmask_b32_e32 v42, v31, v32, vcc
	v_mad_u64_u32 v[42:43], s[24:25], v42, s94, v[8:9]
	ds_read_u16 v53, v42
	v_cndmask_b32_e32 v42, v33, v34, vcc
	v_mad_u64_u32 v[42:43], s[24:25], v42, s94, v[8:9]
	ds_read_u16 v54, v42
	v_cndmask_b32_e32 v42, v35, v36, vcc
	v_mad_u64_u32 v[42:43], s[24:25], v42, s94, v[8:9]
	ds_read_u16 v55, v42
	v_cndmask_b32_e32 v42, v37, v38, vcc
	v_mad_u64_u32 v[42:43], s[24:25], v42, s94, v[8:9]
	ds_read_u16 v56, v42
	s_and_b64 s[24:25], vcc, exec
	v_cndmask_b32_e32 v42, v39, v40, vcc
	s_cselect_b32 s25, s29, s80
	s_cselect_b32 s24, s28, s71
	v_mad_u64_u32 v[42:43], s[36:37], v42, s94, v[8:9]
	s_and_b32 s23, s0, 0x7c0000
	ds_read_u16 v57, v42
	s_waitcnt lgkmcnt(14)
	v_lshl_or_b32 v42, v41, 16, v13
	v_or_b32_e32 v13, s23, v16
	v_lshlrev_b32_e32 v152, 1, v13
	s_and_b32 s16, s16, 0x7c0
	s_waitcnt lgkmcnt(12)
	v_lshl_or_b32 v43, v45, 16, v44
	s_waitcnt lgkmcnt(10)
	v_lshl_or_b32 v44, v47, 16, v46
	s_waitcnt lgkmcnt(6)
	v_lshl_or_b32 v46, v51, 16, v50
	v_lshl_add_u64 v[50:51], s[24:25], 0, v[152:153]
	s_lshl_b32 s26, s16, 1
	v_readlane_b32 s16, v254, 58
	v_lshl_add_u64 v[50:51], v[50:51], 0, s[26:27]
	s_add_i32 s14, s14, s16
	v_readlane_b32 s16, v254, 60
	v_lshl_or_b32 v45, v49, 16, v48
	v_lshl_add_u64 v[50:51], v[10:11], 1, v[50:51]
	s_add_i32 s15, s15, s33
	s_add_i32 s0, s0, s16
	s_and_b64 vcc, exec, s[10:11]
	s_mov_b32 s16, s22
	s_mov_b32 s23, s17
	s_waitcnt lgkmcnt(4)
	v_lshl_or_b32 v47, v53, 16, v52
	s_waitcnt lgkmcnt(2)
	v_lshl_or_b32 v48, v55, 16, v54
	s_waitcnt lgkmcnt(0)
	v_lshl_or_b32 v49, v57, 16, v56
	global_store_dwordx4 v[50:51], v[42:45], off
	global_store_dwordx4 v[50:51], v[46:49], off offset:16
	s_barrier
	s_add_i32 s17, s23, s52
	s_cmpk_gt_i32 s17, 0x7ff
	s_cselect_b64 s[10:11], -1, 0
	s_waitcnt vmcnt(14)
	ds_write_b128 v14, v[116:119]
	ds_write_b128 v14, v[120:123] offset:128
	s_waitcnt lgkmcnt(0)
	s_barrier
; #define LAS __attribute__((address_space(3)))
; __global__ void __launch_bounds__(512, 2) fwd_mega(Args args) {
;     ...
;               for (; idx < 2048; idx += G) {
;                   *(LAS u32x4*)(T + r * QP + 8 * j) = ta; *(LAS u32x4*)(T + r * QP + 64 + 8 * j) = tb;
;                   __syncthreads();
;                   if (idx + G < 2048) { const int i2 = idx + G, rem = i2 & 1023, b_ = rem >> 8, hq = (rem >> 5) & 7, st = rem & 31; const bf16* p = PROJ + (size_t)(b_ * SEQ + 64 * st + r) * PROJW + ((i2 >> 10) ? 4096 : 2048) + 128 * hq + 8 * j;
;                       ta = *(const u32x4*)p; tb = *(const u32x4*)(p + 64); }
;                   unsigned v[16];
; #pragma unroll
;                   for (int i = 0; i < 16; ++i) { const int key = (idx >> 10) ? (16 * kq + i) : (32 * (kq >> 1) + 16 * ((i >> 2) & 1) + 8 * (kq & 1) + 4 * (i >> 3) + (i & 3)); v[i] = T[key * QP + dd]; }
;                   u32x4 o0, o1; o0.x = v[0] | (v[1] << 16); o0.y = v[2] | (v[3] << 16); o0.z = v[4] | (v[5] << 16); o0.w = v[6] | (v[7] << 16);
;                   o1.x = v[8] | (v[9] << 16); o1.y = v[10] | (v[11] << 16); o1.z = v[12] | (v[13] << 16); o1.w = v[14] | (v[15] << 16);
;                   { const int rem = idx & 1023, b_ = rem >> 8, hq = (rem >> 5) & 7, st = rem & 31;
;                     bf16* dst = ((idx >> 10) ? VTG : VTA) + ((size_t)(b_ * 8 + hq) * 128 + dd) * SEQ + 64 * st + 16 * kq;
;                     *(u32x4*)dst = o0; *(u32x4*)(dst + 8) = o1; }
;                   __syncthreads();
	v_readlane_b32 s22, v254, 57
	s_add_i32 s22, s16, s22
	s_cmpk_lt_u32 s23, 0x400
	s_cselect_b64 vcc, -1, 0
	v_cndmask_b32_e32 v13, v10, v15, vcc
	v_mad_u64_u32 v[42:43], s[24:25], v13, s94, v[8:9]
	ds_read_u16 v13, v42
	ds_read_u16 v41, v42 offset:288
	ds_read_u16 v44, v42 offset:576
	ds_read_u16 v45, v42 offset:864
	v_cndmask_b32_e32 v42, v17, v18, vcc
	v_mad_u64_u32 v[42:43], s[24:25], v42, s94, v[8:9]
	ds_read_u16 v46, v42
	v_cndmask_b32_e32 v42, v19, v20, vcc
	v_mad_u64_u32 v[42:43], s[24:25], v42, s94, v[8:9]
	ds_read_u16 v47, v42
	v_cndmask_b32_e32 v42, v21, v22, vcc
	v_mad_u64_u32 v[42:43], s[24:25], v42, s94, v[8:9]
	ds_read_u16 v48, v42
	v_cndmask_b32_e32 v42, v23, v24, vcc
	v_mad_u64_u32 v[42:43], s[24:25], v42, s94, v[8:9]
	ds_read_u16 v49, v42
	v_cndmask_b32_e32 v42, v25, v26, vcc
	v_mad_u64_u32 v[42:43], s[24:25], v42, s94, v[8:9]
	ds_read_u16 v50, v42
	v_cndmask_b32_e32 v42, v27, v28, vcc
	v_mad_u64_u32 v[42:43], s[24:25], v42, s94, v[8:9]
	ds_read_u16 v51, v42
	v_cndmask_b32_e32 v42, v29, v30, vcc
	v_mad_u64_u32 v[42:43], s[24:25], v42, s94, v[8:9]
	ds_read_u16 v52, v42
	v_cndmask_b32_e32 v42, v31, v32, vcc
	v_mad_u64_u32 v[42:43], s[24:25], v42, s94, v[8:9]
	ds_read_u16 v53, v42
	v_cndmask_b32_e32 v42, v33, v34, vcc
	v_mad_u64_u32 v[42:43], s[24:25], v42, s94, v[8:9]
	ds_read_u16 v54, v42
	v_cndmask_b32_e32 v42, v35, v36, vcc
	v_mad_u64_u32 v[42:43], s[24:25], v42, s94, v[8:9]
	ds_read_u16 v55, v42
	v_cndmask_b32_e32 v42, v37, v38, vcc
	v_mad_u64_u32 v[42:43], s[24:25], v42, s94, v[8:9]
	ds_read_u16 v56, v42
	s_and_b64 s[24:25], vcc, exec
	v_cndmask_b32_e32 v42, v39, v40, vcc
	s_cselect_b32 s25, s29, s80
	s_cselect_b32 s24, s28, s71
	v_mad_u64_u32 v[42:43], s[36:37], v42, s94, v[8:9]
	s_and_b32 s23, s0, 0x7c0000
	ds_read_u16 v57, v42
	s_waitcnt lgkmcnt(14)
	v_lshl_or_b32 v42, v41, 16, v13
	v_or_b32_e32 v13, s23, v16
	v_lshlrev_b32_e32 v152, 1, v13
	s_and_b32 s16, s16, 0x7c0
	s_waitcnt lgkmcnt(12)
	v_lshl_or_b32 v43, v45, 16, v44
	s_waitcnt lgkmcnt(10)
	v_lshl_or_b32 v44, v47, 16, v46
	s_waitcnt lgkmcnt(6)
	v_lshl_or_b32 v46, v51, 16, v50
	v_lshl_add_u64 v[50:51], s[24:25], 0, v[152:153]
	s_lshl_b32 s26, s16, 1
	v_readlane_b32 s16, v254, 58
	v_lshl_add_u64 v[50:51], v[50:51], 0, s[26:27]
	s_add_i32 s14, s14, s16
	v_readlane_b32 s16, v254, 60
	v_lshl_or_b32 v45, v49, 16, v48
	v_lshl_add_u64 v[50:51], v[10:11], 1, v[50:51]
	s_add_i32 s15, s15, s33
	s_add_i32 s0, s0, s16
	s_and_b64 vcc, exec, s[10:11]
	s_mov_b32 s16, s22
	s_mov_b32 s23, s17
	s_waitcnt lgkmcnt(4)
	v_lshl_or_b32 v47, v53, 16, v52
	s_waitcnt lgkmcnt(2)
	v_lshl_or_b32 v48, v55, 16, v54
	s_waitcnt lgkmcnt(0)
	v_lshl_or_b32 v49, v57, 16, v56
	global_store_dwordx4 v[50:51], v[42:45], off
	global_store_dwordx4 v[50:51], v[46:49], off offset:16
	s_barrier
	s_add_i32 s17, s23, s52
	s_cmpk_gt_i32 s17, 0x7ff
	s_cselect_b64 s[10:11], -1, 0
	s_waitcnt vmcnt(14)
	ds_write_b128 v14, v[126:129]
	ds_write_b128 v14, v[130:133] offset:128
	s_waitcnt lgkmcnt(0)
	s_barrier
	v_readlane_b32 s22, v254, 57
	s_add_i32 s22, s16, s22
	s_cmpk_lt_u32 s23, 0x400
	s_cselect_b64 vcc, -1, 0
	v_cndmask_b32_e32 v13, v10, v15, vcc
	v_mad_u64_u32 v[42:43], s[24:25], v13, s94, v[8:9]
	ds_read_u16 v13, v42
	ds_read_u16 v41, v42 offset:288
	ds_read_u16 v44, v42 offset:576
	ds_read_u16 v45, v42 offset:864
	v_cndmask_b32_e32 v42, v17, v18, vcc
	v_mad_u64_u32 v[42:43], s[24:25], v42, s94, v[8:9]
	ds_read_u16 v46, v42
	v_cndmask_b32_e32 v42, v19, v20, vcc
	v_mad_u64_u32 v[42:43], s[24:25], v42, s94, v[8:9]
	ds_read_u16 v47, v42
	v_cndmask_b32_e32 v42, v21, v22, vcc
	v_mad_u64_u32 v[42:43], s[24:25], v42, s94, v[8:9]
	ds_read_u16 v48, v42
	v_cndmask_b32_e32 v42, v23, v24, vcc
	v_mad_u64_u32 v[42:43], s[24:25], v42, s94, v[8:9]
	ds_read_u16 v49, v42
	v_cndmask_b32_e32 v42, v25, v26, vcc
	v_mad_u64_u32 v[42:43], s[24:25], v42, s94, v[8:9]
	ds_read_u16 v50, v42
	v_cndmask_b32_e32 v42, v27, v28, vcc
	v_mad_u64_u32 v[42:43], s[24:25], v42, s94, v[8:9]
	ds_read_u16 v51, v42
	v_cndmask_b32_e32 v42, v29, v30, vcc
	v_mad_u64_u32 v[42:43], s[24:25], v42, s94, v[8:9]
	ds_read_u16 v52, v42
	v_cndmask_b32_e32 v42, v31, v32, vcc
	v_mad_u64_u32 v[42:43], s[24:25], v42, s94, v[8:9]
	ds_read_u16 v53, v42
	v_cndmask_b32_e32 v42, v33, v34, vcc
	v_mad_u64_u32 v[42:43], s[24:25], v42, s94, v[8:9]
	ds_read_u16 v54, v42
	v_cndmask_b32_e32 v42, v35, v36, vcc
	v_mad_u64_u32 v[42:43], s[24:25], v42, s94, v[8:9]
	ds_read_u16 v55, v42
	v_cndmask_b32_e32 v42, v37, v38, vcc
	v_mad_u64_u32 v[42:43], s[24:25], v42, s94, v[8:9]
	ds_read_u16 v56, v42
	s_and_b64 s[24:25], vcc, exec
	v_cndmask_b32_e32 v42, v39, v40, vcc
	s_cselect_b32 s25, s29, s80
	s_cselect_b32 s24, s28, s71
	v_mad_u64_u32 v[42:43], s[36:37], v42, s94, v[8:9]
	s_and_b32 s23, s0, 0x7c0000
	ds_read_u16 v57, v42
	s_waitcnt lgkmcnt(14)
	v_lshl_or_b32 v42, v41, 16, v13
	v_or_b32_e32 v13, s23, v16
	v_lshlrev_b32_e32 v152, 1, v13
	s_and_b32 s16, s16, 0x7c0
	s_waitcnt lgkmcnt(12)
	v_lshl_or_b32 v43, v45, 16, v44
	s_waitcnt lgkmcnt(10)
	v_lshl_or_b32 v44, v47, 16, v46
	s_waitcnt lgkmcnt(6)
	v_lshl_or_b32 v46, v51, 16, v50
	v_lshl_add_u64 v[50:51], s[24:25], 0, v[152:153]
	s_lshl_b32 s26, s16, 1
	v_readlane_b32 s16, v254, 58
	v_lshl_add_u64 v[50:51], v[50:51], 0, s[26:27]
	s_add_i32 s14, s14, s16
	v_readlane_b32 s16, v254, 60
	v_lshl_or_b32 v45, v49, 16, v48
	v_lshl_add_u64 v[50:51], v[10:11], 1, v[50:51]
	s_add_i32 s15, s15, s33
	s_add_i32 s0, s0, s16
	s_and_b64 vcc, exec, s[10:11]
	s_mov_b32 s16, s22
	s_mov_b32 s23, s17
	s_waitcnt lgkmcnt(4)
	v_lshl_or_b32 v47, v53, 16, v52
	s_waitcnt lgkmcnt(2)
	v_lshl_or_b32 v48, v55, 16, v54
	s_waitcnt lgkmcnt(0)
	v_lshl_or_b32 v49, v57, 16, v56
	global_store_dwordx4 v[50:51], v[42:45], off
	global_store_dwordx4 v[50:51], v[46:49], off offset:16
	s_barrier
	s_branch .LBB0_153
